# P3 queue: next-item atomic issued at item start, result picked up behind the item's own first load wait
# baseline (speedup 1.0000x reference)
; template<int THRL,class Extra> __device__ __forceinline__ void attn_phase_dyn(char*lds,const AttnTensors&T,unsigned*ctr,const Extra&X,int nextra){
;     ...
;   for(;;){
;     if(tid==0){uw[0]=nxt;}
;     asm volatile("s_waitcnt lgkmcnt(0)\n\ts_barrier":::"memory");
;     const unsigned u=(unsigned)__builtin_amdgcn_readfirstlane((int)uw[0]);
.LBB0_340:
	v_add_u32_e32 v212, s3, v223
	s_waitcnt lgkmcnt(0)
	s_barrier

; template<int THRL> __device__ __forceinline__ void attn_unit(int b,int h,int qb,int j0,f32x4v brow0,f32x4v brow1,unsigned*ctr,unsigned&nxt,const AttnTensors&T_,char*shm){
;     ...
;   const int tid=threadIdx.x,lane=tid&63,r32=lane&31,hi=lane>>5; const int wid=__builtin_amdgcn_readfirstlane(tid>>6);
;   const long rowbase=(long)b*SEQ; const int q0=qb*QB;
;   const bf16*Qw=Q+(rowbase+q0+wid*QBLK)*DM+h*D;
;   const bf16*Kh=K+(rowbase+(long)j0*KVBLK)*DM+h*D,*Vh=V+(rowbase+(long)j0*KVBLK)*DM+h*D;
;   const unsigned lds0=(unsigned)(uintptr_t)shm;
;   float*wsf=(float*)(shm+LDS_WS)+wid*64;
;   const bf16*ksrc=Kh+(long)lane*DM+wid*8;
;   const bf16*vsrc=Vh+(long)(16*(wid&3)+(lane>>2))*DM+(wid>>2)*32+(lane&3)*8;
;   const unsigned kdst=lds0+LDS_K+wid*1024, vdst=lds0+LDS_V+wid*1024;
;     ...
;   const int vb0=(int)(lds0+LDS_V)+((lane>>4)&1)*32+(lane&3)*8+(4*hi+((lane&15)>>2))*64;
;   const char*Kbase=shm+LDS_K; bf16x8 kf[8];
;   const lds_cptr shm3=(lds_cptr)shm; const lds_cptr kp0=shm3+LDS_K+hi*1024+r32*16; const lds_cptr vp0=shm3+LDS_V+((lane>>4)&1)*32+(lane&3)*8+(4*hi+((lane&15)>>2))*64;
;   const int NT=(q0+QB)/KVBLK-j0;
;   DMA_K(0,0);DMA_V(0,0);DMA_K(1,SLOTB);
;   bf16x8 qr[4];
;   #pragma unroll
;   for(int d0=0;d0<4;++d0)qr[d0]=*reinterpret_cast<const bf16x8*>(&Qw[(long)r32*DM+d0*16+hi*8]);
;   float mhat=0.f,l_reg=0.f;f32x16 o[2];o[0]=f32x16{};o[1]=f32x16{};
;   const lds_cptr bp0=shm3+LDS_BIAS+hi*16+j0*256;
;     ...
;   const int qrel=wid*QBLK+r32;
;     ...
;   bool resc=false;
;     ...
;   f32x16 pA0,pA1,pB0,pB1;
;   int sl_prev=0,sl_cur=0,sl_next=SLOTB;
;     ...
;   DMA_K(2,2*SLOTB);
; template<int THRL,class Extra> __device__ __forceinline__ void attn_phase_dyn(char*lds,const AttnTensors&T,unsigned*ctr,const Extra&X,int nextra){
;     ...
;     if(u>=(unsigned)(BATCH*NHEAD*NQB)){ if(tid==0)nxt=G_+__hip_atomic_fetch_add(ctr,1u,__ATOMIC_RELAXED,__HIP_MEMORY_SCOPE_AGENT);
;       X((int)u-BATCH*NHEAD*NQB); asm volatile("s_waitcnt lgkmcnt(0)\n\ts_barrier":::"memory"); continue; }
;     const int qb=NQB-1-(int)(u/(BATCH*NHEAD)), bh=(int)(u%(BATCH*NHEAD));
;     const int j0=__builtin_amdgcn_readfirstlane((int)jt[bh*NQB+qb]);
;     const f32x4v*src=(const f32x4v*)((const float*)(T.ws+T.obias)+(long)bh*SEQ)+tid*2; const f32x4v ba=src[0],bb=src[1];
;     attn_unit<THRL>(bh/NHEAD,bh%NHEAD,qb,j0,ba,bb,ctr,nxt,T,lds);
.LBB0_343:
	s_and_saveexec_b64 s[6:7], s[18:19]
	ds_write_b32 v201, v213 offset:49152
	s_or_b64 exec, exec, s[6:7]
	s_waitcnt lgkmcnt(0)
	s_barrier
	ds_read_b32 v1, v201 offset:49152
	s_mov_b64 s[6:7], -1
	s_waitcnt lgkmcnt(0)
	v_readfirstlane_b32 s63, v1
	s_cmpk_gt_u32 s63, 0x57f
	s_cbranch_scc1 .LBB0_342
	s_cmpk_lt_u32 s63, 0x400
	s_cbranch_scc0 .LBB0_361
	s_and_saveexec_b64 s[8:9], s[18:19]
	s_cbranch_execz .Lqpop_a
	v_mov_b32_e32 v186, 1
	global_atomic_add v186, v201, v186, s[14:15] sc0
.Lqpop_a:
	s_or_b64 exec, exec, s[8:9]
	s_and_b32 s6, s63, 63
	s_lshr_b32 s44, s63, 6
	s_lshl_b32 s7, s6, 6
	s_add_i32 s7, s7, 0
	s_lshl_b32 s8, s44, 2
	s_sub_i32 s7, s7, s8
	s_add_i32 s7, s7, 0x1883c
	s_lshl_b32 s12, s6, 14
	v_mov_b32_e32 v1, s7
	s_sub_i32 s7, 15, s44
	v_lshl_add_u64 v[6:7], v[208:209], 0, s[12:13]
	s_bfe_u32 s12, s63, 0x30003
	v_readfirstlane_b32 s66, v0
	s_lshr_b32 s65, s66, 6
	s_lshl_b32 s8, s12, 12
	s_lshl_b32 s45, s7, 8
	s_or_b32 s7, s45, s8
	s_lshl_b32 s69, s65, 5
	s_add_i32 s10, s7, s69
	s_mov_b32 s11, s13
	ds_read_b32 v1, v1
	s_lshl_b64 s[8:9], s[10:11], 10
	s_add_u32 s7, s47, s8
	s_addc_u32 s9, s48, s9
	s_lshl_b32 s8, s63, 6
	s_and_b32 s8, s8, 0x1c0
	s_lshl_b32 s64, s8, 1
	s_waitcnt lgkmcnt(0)
	v_readfirstlane_b32 s6, v1
	s_add_u32 s8, s7, s64
	s_addc_u32 s9, s9, 0
	s_ashr_i32 s7, s6, 31
	s_lshl_b64 s[40:41], s[6:7], 15
	s_lshl_b32 s7, s12, 21
	s_add_u32 s40, s40, s7
	s_addc_u32 s41, s41, 0
	s_lshl_b64 s[40:41], s[40:41], 1
	s_add_u32 s7, s49, s40
	s_addc_u32 s12, s50, s41
	s_add_u32 s42, s7, s64
	s_addc_u32 s43, s12, 0
	s_add_u32 s7, s51, s40
	s_addc_u32 s12, s52, s41
	s_add_u32 s40, s7, s64
	s_addc_u32 s41, s12, 0
	s_lshr_b32 s7, s66, 2
	v_bfe_u32 v1, v0, 2, 4
	v_mov_b32_e32 v235, v201
	v_and_or_b32 v1, s7, 48, v1
	v_lshl_add_u64 v[10:11], s[42:43], 0, v[234:235]
	s_lshl_b32 s12, s65, 4
	v_lshlrev_b32_e32 v200, 10, v1
	v_lshl_add_u64 v[226:227], v[10:11], 0, s[12:13]
	v_lshl_add_u64 v[10:11], s[40:41], 0, v[200:201]
	s_and_b32 s12, s7, 0x3fffffc0
	v_lshl_add_u64 v[10:11], v[10:11], 0, s[12:13]
	s_lshl_b32 s12, s65, 10
	s_cmp_lg_u32 0, -1
	s_cselect_b32 s7, 0, 0
	global_load_dwordx4 v[2:5], v[6:7], off offset:16
	s_nop 0
	global_load_dwordx4 v[6:9], v[6:7], off
	s_and_b32 s88, s63, 63
	s_lshl_b32 s88, s88, 14
	s_lshl_b32 s89, s45, 2
	s_add_i32 s88, s88, s89
	s_addk_i32 s88, 0x200
	v_mov_b32_e32 v231, s88
	global_load_dword v231, v231, s[86:87]
	v_mov_b32_e32 v215, v201
	s_add_i32 s67, s12, s7
	s_mov_b32 s7, m0
	s_mov_b32 m0, s67
	s_nop 0
	global_load_lds_dwordx4 v[226:227], off
	s_mov_b32 m0, s7
	v_lshl_add_u64 v[228:229], v[10:11], 0, v[214:215]
	s_add_i32 s68, s67, 0x6000
	s_mov_b32 s7, m0
	s_mov_b32 m0, s68
	s_nop 0
	global_load_lds_dwordx4 v[228:229], off
	s_mov_b32 m0, s7
	v_lshl_add_u64 v[10:11], v[226:227], 0, s[16:17]
	s_add_i32 s7, s67, 0x2000
	s_mov_b32 s40, m0
	s_mov_b32 m0, s7
	s_nop 0
	global_load_lds_dwordx4 v[10:11], off
	s_mov_b32 m0, s40
	global_load_dwordx4 v[126:129], v255, s[8:9]
	global_load_dwordx4 v[122:125], v255, s[8:9] offset:32
	global_load_dwordx4 v[118:121], v255, s[8:9] offset:64
	global_load_dwordx4 v[114:117], v255, s[8:9] offset:96
	v_lshl_add_u64 v[10:11], v[226:227], 0, s[20:21]
	s_add_i32 s7, s67, 0x4000
	s_mov_b32 s8, m0
	s_mov_b32 m0, s7
	s_nop 0
	global_load_lds_dwordx4 v[10:11], off
	s_mov_b32 m0, s8
	v_add_u32_e32 v1, 0, v202
	v_add_u32_e32 v1, 0x14800, v1
	v_mov_b32_e32 v212, v213
	s_waitcnt vmcnt(4)
	v_add_f32_e32 v231, v237, v231
	v_sub_f32_e32 v2, v2, v231
	v_sub_f32_e32 v3, v3, v231
	v_sub_f32_e32 v4, v4, v231
	v_sub_f32_e32 v5, v5, v231
	v_sub_f32_e32 v6, v6, v231
	v_sub_f32_e32 v7, v7, v231
	v_sub_f32_e32 v8, v8, v231
	v_sub_f32_e32 v9, v9, v231
	ds_write_b128 v1, v[6:9]
	ds_write_b128 v1, v[2:5] offset:16
	v_add_u32_e32 v212, s3, v186
	s_lshl_b32 s8, s45, 2
	v_or_b32_e32 v200, s69, v205
	s_add_i32 s8, s8, 0
	v_lshl_add_u32 v1, v200, 2, s8
	s_lshl_b32 s7, s6, 8
	s_waitcnt vmcnt(3) lgkmcnt(0)
	s_barrier
;   #define BINIT(P0,P1,t) do{ _Pragma("unroll") for(int g_=0;g_<4;++g_){BL(P0,t,g_,0);BL(P1,t,g_,128);} _Pragma("unroll") for(int g_=0;g_<4;++g_){BS(P0,g_);BS(P1,g_);} }while(0)
;   #define CMASK(P0,P1,t) do{int jb_=(t)-(NT-4); if(jb_>=0)cmask(P0,P1,jb_,qrel,hi);}while(0)
;   #define CMASK(P0,P1,t) do{}while(0)
;   #define CMASK(P0,P1,t) do{int jb_=(t)-(NT-4); if(jb_>=0)cmask(P0,P1,jb_,qrel,hi);}while(0)
; __device__ __forceinline__ void cmask(f32x16&p0,f32x16&p1,int jb,int qrel,int hi){
;   const float NEG=-INFINITY; int kb=64*jb+4*hi;
;   #pragma unroll
;   for(int r=0;r<16;++r){int kv=kb+(r&3)+8*(r>>2); if(kv>qrel)p0[r]=NEG; if(kv+32>qrel)p1[r]=NEG;}
; }
; template<int THRL> __device__ __forceinline__ void attn_unit(int b,int h,int qb,int j0,f32x4v brow0,f32x4v brow1,unsigned*ctr,unsigned&nxt,const AttnTensors&T_,char*shm){
;     ...
;   mhat=((const __attribute__((address_space(3))) float*)(shm3+LDS_BIAS))[q0+qrel]+T_.hdr;
;   BINIT(pA0,pA1,0);
;   qkt(pA0,pA1,Kbase,qr,r32,hi);asm volatile("s_nop 15\n\ts_nop 7":"+v"(pA0),"+v"(pA1));CMASK(pA0,pA1,0);
	v_add_u32_e32 v2, 0x14800, v1
	v_add_u32_e32 v1, s7, v240
	ds_read_b32 v18, v2
	ds_read_b128 v[2:5], v1
	ds_read_b128 v[6:9], v1 offset:32
	ds_read_b128 v[10:13], v1 offset:64
	ds_read_b128 v[34:37], v1 offset:128
	ds_read_b128 v[14:17], v1 offset:96
	ds_read_b128 v[38:41], v1 offset:160
	ds_read_b128 v[42:45], v1 offset:192
	ds_read_b128 v[46:49], v1 offset:224
	s_waitcnt lgkmcnt(8)
	v_mov_b32_e32 v230, 0
	s_waitcnt lgkmcnt(7)
	v_sub_f32_e32 v21, v5, v230
	v_sub_f32_e32 v20, v4, v230
	v_sub_f32_e32 v19, v3, v230
	v_sub_f32_e32 v18, v2, v230
	ds_read_b128 v[2:5], v207
	s_waitcnt lgkmcnt(6)
	v_sub_f32_e32 v29, v13, v230
	v_sub_f32_e32 v28, v12, v230
	v_sub_f32_e32 v27, v11, v230
	v_sub_f32_e32 v26, v10, v230
	s_waitcnt lgkmcnt(2)
	v_sub_f32_e32 v13, v45, v230
	v_sub_f32_e32 v12, v44, v230
	v_sub_f32_e32 v11, v43, v230
	v_sub_f32_e32 v10, v42, v230
	ds_read_b128 v[42:45], v207 offset:512
	v_sub_f32_e32 v33, v17, v230
	v_sub_f32_e32 v32, v16, v230
	v_sub_f32_e32 v31, v15, v230
	v_sub_f32_e32 v30, v14, v230
	v_sub_f32_e32 v25, v9, v230
	v_sub_f32_e32 v24, v8, v230
	v_sub_f32_e32 v23, v7, v230
	v_sub_f32_e32 v22, v6, v230
	s_waitcnt lgkmcnt(2)
	v_sub_f32_e32 v17, v49, v230
	v_sub_f32_e32 v16, v48, v230
	v_sub_f32_e32 v15, v47, v230
	v_sub_f32_e32 v14, v46, v230
	v_sub_f32_e32 v9, v41, v230
	s_waitcnt vmcnt(3) lgkmcnt(1)
	v_mfma_f32_32x32x16_bf16 v[18:33], v[2:5], v[126:129], v[18:33]
	v_sub_f32_e32 v8, v40, v230
	v_sub_f32_e32 v7, v39, v230
	v_sub_f32_e32 v6, v38, v230
	v_sub_f32_e32 v5, v37, v230
	v_sub_f32_e32 v4, v36, v230
	v_sub_f32_e32 v3, v35, v230
	v_sub_f32_e32 v2, v34, v230
	ds_read_b128 v[34:37], v207 offset:2048
	ds_read_b128 v[38:41], v207 offset:2560
	s_waitcnt lgkmcnt(2)
	v_mfma_f32_32x32x16_bf16 v[2:17], v[42:45], v[126:129], v[2:17]
	s_addk_i32 s45, 0x100
	s_lshr_b32 s8, s45, 6
	s_lshl_b64 s[40:41], s[10:11], 9
	s_sub_i32 s69, s8, s6
	s_cmp_gt_i32 s69, 4
	s_waitcnt vmcnt(2) lgkmcnt(1)
	v_mfma_f32_32x32x16_bf16 v[18:33], v[34:37], v[122:125], v[18:33]
	s_waitcnt lgkmcnt(0)
	v_mfma_f32_32x32x16_bf16 v[2:17], v[38:41], v[122:125], v[2:17]
	ds_read_b128 v[34:37], v207 offset:4096
	ds_read_b128 v[38:41], v207 offset:4608
	s_waitcnt vmcnt(1) lgkmcnt(1)
	v_mfma_f32_32x32x16_bf16 v[18:33], v[34:37], v[118:121], v[18:33]
	s_waitcnt lgkmcnt(0)
	v_mfma_f32_32x32x16_bf16 v[2:17], v[38:41], v[118:121], v[2:17]
	ds_read_b128 v[34:37], v207 offset:6144
	ds_read_b128 v[38:41], v207 offset:6656
	s_waitcnt vmcnt(0) lgkmcnt(1)
	v_mfma_f32_32x32x16_bf16 v[18:33], v[34:37], v[114:117], v[18:33]
	s_waitcnt lgkmcnt(0)
	v_mfma_f32_32x32x16_bf16 v[2:17], v[38:41], v[114:117], v[2:17]
	s_nop 15
	s_nop 7
	s_cbranch_scc1 .LBB0_353
	s_lshl_b32 s9, s69, 6
	v_subrev_u32_e32 v34, s9, v232
	v_add_u32_e32 v36, 0x120, v34
	v_add_u32_e32 v35, 0x100, v34
	v_cmp_le_i32_e32 vcc, v36, v200
	s_nop 5
	v_cndmask_b32_e32 v2, v252, v2, vcc
	v_cmp_lt_i32_e32 vcc, v35, v200
	s_nop 1
	v_cndmask_b32_e32 v19, v252, v19, vcc
	v_cmp_le_i32_e32 vcc, v35, v200
	v_add_u32_e32 v35, 0x121, v34
	s_nop 0
	v_cndmask_b32_e32 v18, v252, v18, vcc
	v_cmp_le_i32_e32 vcc, v35, v200
	v_add_u32_e32 v35, 0x102, v34
	s_nop 0
	v_cndmask_b32_e32 v3, v252, v3, vcc
	v_cmp_le_i32_e32 vcc, v35, v200
	v_add_u32_e32 v35, 0x122, v34
	s_nop 0
	v_cndmask_b32_e32 v20, v252, v20, vcc
	v_cmp_le_i32_e32 vcc, v35, v200
	v_add_u32_e32 v35, 0x103, v34
	s_nop 0
	v_cndmask_b32_e32 v4, v252, v4, vcc
	v_cmp_le_i32_e32 vcc, v35, v200
	v_add_u32_e32 v35, 0x123, v34
	s_nop 0
	v_cndmask_b32_e32 v21, v252, v21, vcc
	v_cmp_le_i32_e32 vcc, v35, v200
	v_add_u32_e32 v35, 0x108, v34
	s_nop 0
	v_cndmask_b32_e32 v5, v252, v5, vcc
	v_cmp_le_i32_e32 vcc, v35, v200
	v_add_u32_e32 v35, 0x128, v34
	s_nop 0
	v_cndmask_b32_e32 v22, v252, v22, vcc
	v_cmp_le_i32_e32 vcc, v35, v200
	v_add_u32_e32 v35, 0x109, v34
	s_nop 0
	v_cndmask_b32_e32 v6, v252, v6, vcc
	v_cmp_le_i32_e32 vcc, v35, v200
	v_add_u32_e32 v35, 0x129, v34
	s_nop 0
	v_cndmask_b32_e32 v23, v252, v23, vcc
	v_cmp_le_i32_e32 vcc, v35, v200
	v_add_u32_e32 v35, 0x10a, v34
	s_nop 0
	v_cndmask_b32_e32 v7, v252, v7, vcc
	v_cmp_le_i32_e32 vcc, v35, v200
	v_add_u32_e32 v35, 0x12a, v34
	s_nop 0
	v_cndmask_b32_e32 v24, v252, v24, vcc
	v_cmp_le_i32_e32 vcc, v35, v200
	v_add_u32_e32 v35, 0x10b, v34
	s_nop 0
	v_cndmask_b32_e32 v8, v252, v8, vcc
	v_cmp_le_i32_e32 vcc, v35, v200
	v_add_u32_e32 v35, 0x12b, v34
	s_nop 0
	v_cndmask_b32_e32 v25, v252, v25, vcc
	v_cmp_le_i32_e32 vcc, v35, v200
	v_add_u32_e32 v35, 0x110, v34
	s_nop 0
	v_cndmask_b32_e32 v9, v252, v9, vcc
	v_cmp_le_i32_e32 vcc, v35, v200
	v_add_u32_e32 v35, 0x130, v34
	s_nop 0
	v_cndmask_b32_e32 v26, v252, v26, vcc
	v_cmp_le_i32_e32 vcc, v35, v200
	v_add_u32_e32 v35, 0x111, v34
	s_nop 0
	v_cndmask_b32_e32 v10, v252, v10, vcc
	v_cmp_le_i32_e32 vcc, v35, v200
	v_add_u32_e32 v35, 0x131, v34
	s_nop 0
	v_cndmask_b32_e32 v27, v252, v27, vcc
	v_cmp_le_i32_e32 vcc, v35, v200
	v_add_u32_e32 v35, 0x112, v34
	s_nop 0
	v_cndmask_b32_e32 v11, v252, v11, vcc
	v_cmp_le_i32_e32 vcc, v35, v200
	v_add_u32_e32 v35, 0x132, v34
	s_nop 0
	v_cndmask_b32_e32 v28, v252, v28, vcc
	v_cmp_le_i32_e32 vcc, v35, v200
	v_add_u32_e32 v35, 0x113, v34
	s_nop 0
	v_cndmask_b32_e32 v12, v252, v12, vcc
	v_cmp_le_i32_e32 vcc, v35, v200
	v_add_u32_e32 v35, 0x133, v34
	s_nop 0
	v_cndmask_b32_e32 v29, v252, v29, vcc
	v_cmp_le_i32_e32 vcc, v35, v200
	v_add_u32_e32 v35, 0x118, v34
	s_nop 0
	v_cndmask_b32_e32 v13, v252, v13, vcc
	v_cmp_le_i32_e32 vcc, v35, v200
	v_add_u32_e32 v35, 0x138, v34
	s_nop 0
	v_cndmask_b32_e32 v30, v252, v30, vcc
	v_cmp_le_i32_e32 vcc, v35, v200
	v_add_u32_e32 v35, 0x119, v34
	s_nop 0
	v_cndmask_b32_e32 v14, v252, v14, vcc
	v_cmp_le_i32_e32 vcc, v35, v200
	v_add_u32_e32 v35, 0x139, v34
	s_nop 0
	v_cndmask_b32_e32 v31, v252, v31, vcc
	v_cmp_le_i32_e32 vcc, v35, v200
	v_add_u32_e32 v35, 0x11a, v34
	s_nop 0
	v_cndmask_b32_e32 v15, v252, v15, vcc
	v_cmp_le_i32_e32 vcc, v35, v200
	v_add_u32_e32 v35, 0x13a, v34
	s_nop 0
	v_cndmask_b32_e32 v32, v252, v32, vcc
	v_cmp_le_i32_e32 vcc, v35, v200
	v_add_u32_e32 v35, 0x11b, v34
	v_add_u32_e32 v34, 0x13b, v34
	v_cndmask_b32_e32 v16, v252, v16, vcc
	v_cmp_le_i32_e32 vcc, v35, v200
	s_nop 1
	v_cndmask_b32_e32 v33, v252, v33, vcc
	v_cmp_le_i32_e32 vcc, v34, v200
	s_nop 1
	v_cndmask_b32_e32 v17, v252, v17, vcc

; template<int THRL,class Extra> __device__ __forceinline__ void attn_phase_dyn(char*lds,const AttnTensors&T,unsigned*ctr,const Extra&X,int nextra){
;     ...
;     if(u>=(unsigned)(BATCH*NHEAD*NQB)){ if(tid==0)nxt=G_+__hip_atomic_fetch_add(ctr,1u,__ATOMIC_RELAXED,__HIP_MEMORY_SCOPE_AGENT);
;       X((int)u-BATCH*NHEAD*NQB); asm volatile("s_waitcnt lgkmcnt(0)\n\ts_barrier":::"memory"); continue; }
;     __device__ __forceinline__ void operator()(int item) const {
;     ...
;         const int m0 = item * 128 + wave * 16; const int ch = 8 * lane;
;         float w0[8], w1[8], w2[8];
; #pragma unroll
;         for (int e = 0; e < 8; ++e) { w0[e] = conv_w[ch + e]; w1[e] = conv_w[CW + ch + e]; w2[e] = conv_w[2 * CW + ch + e]; }
;         float p1[8], p2[8];
;         const bool first = (m0 % T) == 0;
;         { v4u a = {0u, 0u, 0u, 0u}, bq = {0u, 0u, 0u, 0u};
;           if (!first) { a = *(const v4u*)(CUB + (size_t)(m0 - 2) * CW + ch); bq = *(const v4u*)(CUB + (size_t)(m0 - 1) * CW + ch); }
.LBB0_361:
	s_and_b64 vcc, exec, s[6:7]
	s_cbranch_vccz .LBB0_341
	s_and_saveexec_b64 s[6:7], s[18:19]
	s_cbranch_execz .LBB0_366
	v_mov_b32_e32 v223, 1
	global_atomic_add v223, v201, v223, s[14:15] sc0
.LBB0_366:
	s_or_b64 exec, exec, s[6:7]
	s_mov_b64 s[40:41], s[0:1]
	s_load_dwordx2 s[6:7], s[40:41], 0x70
	v_readfirstlane_b32 s44, v0
	s_addk_i32 s63, 0xfc00
	s_lshr_b32 s42, s44, 6
	s_cmpk_lt_u32 s63, 0x100
	s_mov_b64 s[8:9], -1
	s_cbranch_scc0 .LBB0_423
	s_load_dwordx2 s[8:9], s[40:41], 0x48
	v_lshlrev_b32_e32 v200, 2, v206
	s_waitcnt lgkmcnt(0)
	global_load_dwordx4 v[2:5], v200, s[8:9] offset:16
	global_load_dwordx4 v[6:9], v200, s[8:9]
	global_load_dwordx4 v[10:13], v200, s[8:9] offset:2064
	global_load_dwordx4 v[14:17], v200, s[8:9] offset:2048
	v_lshl_add_u64 v[18:19], s[8:9], 0, v[200:201]
	v_lshl_add_u64 v[22:23], v[18:19], 0, s[30:31]
	v_add_co_u32_e32 v18, vcc, 0x1000, v18
	s_lshl_b32 s8, s42, 4
	s_nop 0
	v_addc_co_u32_e32 v19, vcc, 0, v19, vcc
	global_load_dwordx4 v[18:21], v[18:19], off
	s_nop 0
	global_load_dwordx4 v[22:25], v[22:23], off offset:16
	s_lshl_b32 s9, s63, 7
	s_add_i32 s12, s8, s9
	s_and_b32 s8, s12, 0xff0
	s_cmp_eq_u32 s8, 0
	s_cbranch_scc1 .LBB0_419
	s_add_u32 s43, s6, 0xe000000
	s_addc_u32 s45, s7, 0
	s_add_i32 s8, s12, -2
	s_mov_b32 s9, s13
	s_lshl_b64 s[8:9], s[8:9], 10
	s_add_u32 s8, s43, s8
	s_addc_u32 s9, s45, s9
	s_add_i32 s10, s12, -1
	s_mov_b32 s11, s13
	s_lshl_b64 s[10:11], s[10:11], 10
	v_lshlrev_b32_e32 v1, 1, v206
	s_add_u32 s10, s43, s10
	s_addc_u32 s11, s45, s11
	global_load_dwordx4 v[30:33], v1, s[8:9]
	global_load_dwordx4 v[26:29], v1, s[10:11]
	s_branch .LBB0_420
